# v17_zerotrim
# baseline (speedup 1.0000x reference)
.LBB0_1372:
	s_add_i32 s40, s84, -2
	s_min_i32 s24, s40, 0x100
	s_lshl_b64 s[12:13], s[24:25], 13
	s_lshl_b32 s24, s83, 13
	s_add_i32 m0, s74, s24
	s_min_i32 s24, s40, 0xff
	s_lshl_b64 s[40:41], s[24:25], 14
	s_cmp_eq_u32 s84, 1
	s_cselect_b32 s13, 0, s13
	s_cselect_b32 s12, 0, s12
	v_lshl_add_u64 v[80:81], v[134:135], 0, s[12:13]
	s_cselect_b32 s13, 0, s41
	s_cselect_b32 s12, 0, s40
	global_load_lds_dwordx4 v[80:81], off
	v_lshl_add_u64 v[80:81], v[132:133], 0, s[12:13]
	s_lshl_b32 s12, s83, 14
	s_add_i32 s12, s74, s12
	s_add_i32 m0, s12, 0x6000
	v_lshl_add_u32 v126, s81, 13, v153
	global_load_lds_dwordx4 v[80:81], off
	v_lshl_add_u64 v[80:81], v[80:81], 0, s[26:27]
	s_add_i32 m0, s12, 0x8000
	s_lshl_b32 s12, s81, 8
	global_load_lds_dwordx4 v[80:81], off
	v_add_u32_e32 v115, v126, v152
	v_add_u32_e32 v114, s12, v154
	ds_read_b128 v[208:211], v115 offset:4096
	ds_read_b128 v[80:83], v114 offset:128
	ds_read_b128 v[84:87], v114 offset:144
	ds_read_b128 v[88:91], v114 offset:192
	ds_read_b128 v[92:95], v114 offset:208
	ds_read_b128 v[224:227], v115
	ds_read_b128 v[192:195], v114
	ds_read_b128 v[196:199], v114 offset:16
	ds_read_b128 v[200:203], v114 offset:64
	ds_read_b128 v[204:207], v114 offset:80
	v_med3_i32 v118, v113, 0, v137
	v_lshlrev_b32_e32 v119, 2, v118
	global_load_dword v164, v119, s[54:55]
	v_add_u32_e32 v116, v126, v155
	v_add_u32_e32 v117, v126, v156
	v_add_u32_e32 v118, v126, v157
	s_waitcnt lgkmcnt(5)
	v_mfma_f32_32x32x16_bf16 v[80:95], v[208:211], v[108:111], v[80:95]
	ds_read_b128 v[212:215], v116 offset:4096
	ds_read_b128 v[228:231], v116
	s_waitcnt lgkmcnt(2)
	v_mfma_f32_32x32x16_bf16 v[192:207], v[224:227], v[108:111], v[192:207]
	ds_read_b128 v[216:219], v117 offset:4096
	ds_read_b128 v[232:235], v117
	s_waitcnt lgkmcnt(3)
	v_mfma_f32_32x32x16_bf16 v[80:95], v[212:215], v[104:107], v[80:95]
	s_waitcnt lgkmcnt(2)
	v_mfma_f32_32x32x16_bf16 v[192:207], v[228:231], v[104:107], v[192:207]
	ds_read_b128 v[220:223], v118 offset:4096
	ds_read_b128 v[236:239], v118
	s_waitcnt lgkmcnt(3)
	v_mfma_f32_32x32x16_bf16 v[80:95], v[216:219], v[100:103], v[80:95]
	s_waitcnt lgkmcnt(2)
	v_mfma_f32_32x32x16_bf16 v[192:207], v[232:235], v[100:103], v[192:207]
	s_waitcnt lgkmcnt(1)
	v_mfma_f32_32x32x16_bf16 v[80:95], v[220:223], v[96:99], v[80:95]
	s_waitcnt lgkmcnt(0)
	v_mfma_f32_32x32x16_bf16 v[192:207], v[236:239], v[96:99], v[192:207]
	s_nop 9
	v_max_f32_e32 v119, v81, v81
	v_max_f32_e32 v120, v80, v80
	v_max_f32_e32 v119, v120, v119
	v_max3_f32 v119, v119, v82, v83
	v_max_f32_e32 v240, v193, v193
	v_max_f32_e32 v241, v192, v192
	v_max3_f32 v119, v119, v84, v85
	v_max_f32_e32 v240, v241, v240
	v_max3_f32 v119, v119, v86, v87
	v_max3_f32 v240, v240, v194, v195
	v_max3_f32 v119, v119, v88, v89
	v_max3_f32 v240, v240, v196, v197
	v_max3_f32 v119, v119, v90, v91
	v_max3_f32 v240, v240, v198, v199
	v_max3_f32 v119, v119, v92, v93
	v_max3_f32 v240, v240, v200, v201
	v_max3_f32 v119, v119, v94, v95
	v_max3_f32 v240, v240, v202, v203
	v_max3_f32 v240, v240, v204, v205
	v_max3_f32 v240, v240, v206, v207
	v_cmp_lt_f32_e32 vcc, v119, v112
	s_cmp_eq_u64 vcc, exec
	s_cbranch_scc0 .LBB0_1377
	s_and_b64 vcc, exec, s[8:9]
	s_cbranch_vccnz .LBB0_1375
	v_sub_u32_e32 v242, v148, v131
	v_cvt_f32_i32_e32 v242, v242
	v_lshl_add_u32 v243, s80, 8, v160
	v_mul_f32_e32 v242, v139, v242
	ds_write_b32 v243, v242
.LBB0_1375:
	s_add_i32 s24, s84, -1
	s_mov_b32 s12, s80
	s_cmp_lt_i32 s84, 2
	s_waitcnt vmcnt(4) lgkmcnt(0)
	s_barrier
	v_subrev_u32_e32 v113, 64, v113
	s_mov_b64 s[42:43], 0
	s_mov_b64 s[40:41], s[10:11]
	s_waitcnt vmcnt(0)
	v_mov_b32_e32 v148, v164
	s_mov_b32 s80, s83
	s_mov_b32 s83, s81
	s_mov_b32 s84, 0
	s_cselect_b64 s[44:45], -1, 0
	s_mov_b32 s81, s12
	s_and_b64 vcc, exec, s[44:45]
	s_cbranch_vccz .LBB0_1378
	v_mov_b32_e32 v241, v240
	s_nop 1
	v_permlane32_swap_b32_e32 v240, v241
	v_max_f32_e32 v241, v241, v241
	v_max_f32_e32 v240, v240, v240
	v_max_f32_e32 v166, v240, v241
	v_mov_b64_e32 v[64:65], v[192:193]
	v_mov_b64_e32 v[66:67], v[194:195]
	v_mov_b64_e32 v[68:69], v[196:197]
	v_mov_b64_e32 v[70:71], v[198:199]
	v_mov_b64_e32 v[72:73], v[200:201]
	v_mov_b64_e32 v[74:75], v[202:203]
	v_mov_b64_e32 v[76:77], v[204:205]
	v_mov_b64_e32 v[78:79], v[206:207]
	s_branch .LBB0_1330

.LBB0_1378:
	s_mov_b32 s84, s24
	v_cmp_lt_f32_e32 vcc, v240, v112
	s_cmp_lg_u64 vcc, exec
	s_cbranch_scc1 .Lz_fix2
	s_branch .LBB0_1372
.Lz_fix2:
	v_mov_b32_e32 v241, v240
	s_nop 1
	v_permlane32_swap_b32_e32 v240, v241
	v_max_f32_e32 v241, v241, v241
	v_max_f32_e32 v240, v240, v240
	v_max_f32_e32 v166, v240, v241
	v_mov_b64_e32 v[64:65], v[192:193]
	v_mov_b64_e32 v[66:67], v[194:195]
	v_mov_b64_e32 v[68:69], v[196:197]
	v_mov_b64_e32 v[70:71], v[198:199]
	v_mov_b64_e32 v[72:73], v[200:201]
	v_mov_b64_e32 v[74:75], v[202:203]
	v_mov_b64_e32 v[76:77], v[204:205]
	v_mov_b64_e32 v[78:79], v[206:207]
	s_branch .LBB0_1376
